# attn K/V staging interleaved into MFMA stream + pass C gate loads batched (8 serialized RTTs removed)
# speedup vs baseline: 1.0055x; 1.0046x over previous
.LBB0_631:
	s_add_i32 s10, s11, 1
	s_bitcmp1_b32 s10, 0
	s_cselect_b32 s16, 0xac00, 0
	s_add_i32 s16, s16, 0
	v_add_u32_e32 v247, s16, v233
	v_add_u32_e32 v248, s16, v234
	v_add_u32_e32 v249, s16, v236
	v_add_u32_e32 v250, s16, v208
	v_add_u32_e32 v251, s16, v200
	s_cmp_lt_u32 s11, s7
	s_cselect_b64 s[16:17], -1, 0
	s_cmp_lg_u64 s[16:17], 0
	s_addc_u32 s6, s6, 0
	s_mov_b32 s22, s14
	s_mov_b32 s23, s15
	s_mov_b32 s26, s14
	s_mov_b32 s27, s15
	s_cmp_gt_i32 s11, s1
	s_cbranch_scc1 .Lattn1_stage_only
	s_bitcmp1_b32 s11, 0
	s_cselect_b32 s11, 0xac00, 0
	s_add_i32 s11, s11, 0
	v_mov_b32_e32 v80, v213
	v_add3_u32 v0, s11, v180, v229
	ds_read_b128 v[2:5], v0
	ds_read_b128 v[6:9], v0 offset:32
	ds_read_b128 v[10:13], v0 offset:64
	ds_read_b128 v[184:187], v0 offset:96
	ds_read_b128 v[188:191], v0 offset:128
	ds_read_b128 v[192:195], v0 offset:160
	v_mov_b32_e32 v81, v80
	v_mov_b32_e32 v82, v80
	v_mov_b32_e32 v83, v80
	v_mov_b32_e32 v84, v80
	v_mov_b32_e32 v85, v80
	v_mov_b32_e32 v86, v80
	v_mov_b32_e32 v87, v80
	v_mov_b32_e32 v88, v80
	v_mov_b32_e32 v89, v80
	v_mov_b32_e32 v90, v80
	v_mov_b32_e32 v91, v80
	v_mov_b32_e32 v92, v80
	v_mov_b32_e32 v93, v80
	v_mov_b32_e32 v94, v80
	v_mov_b32_e32 v95, v80
	ds_read_b128 v[196:199], v0 offset:192
	s_waitcnt lgkmcnt(6)
	v_mfma_f32_32x32x16_bf16 v[96:111], v[2:5], v[132:135], v[80:95]
	s_mul_i32 s16, s6, 0x6000
	s_waitcnt vmcnt(4)
	ds_write_b128 v247, v[112:115]
	buffer_load_dwordx4 v[112:115], v230, s[20:23], s16 offen
	ds_read_b128 v[2:5], v0 offset:224
	s_waitcnt lgkmcnt(6)
	v_mfma_f32_32x32x16_bf16 v[96:111], v[6:9], v[136:139], v[96:111]
	ds_read_b128 v[6:9], v0 offset:256
	s_waitcnt lgkmcnt(6)
	v_mfma_f32_32x32x16_bf16 v[96:111], v[10:13], v[140:143], v[96:111]
	s_add_i32 s17, s16, 0x2000
	s_waitcnt vmcnt(4)
	ds_write_b128 v248, v[116:119]
	buffer_load_dwordx4 v[116:119], v230, s[20:23], s17 offen
	ds_read_b128 v[10:13], v0 offset:288
	s_waitcnt lgkmcnt(6)
	v_mfma_f32_32x32x16_bf16 v[96:111], v[184:187], v[144:147], v[96:111]
	ds_read_b128 v[184:187], v0 offset:320
	s_waitcnt lgkmcnt(6)
	v_mfma_f32_32x32x16_bf16 v[96:111], v[188:191], v[152:155], v[96:111]
	s_addk_i32 s16, 0x4000
	s_waitcnt vmcnt(4)
	ds_write_b128 v249, v[120:123]
	buffer_load_dwordx4 v[120:123], v230, s[20:23], s16 offen
	ds_read_b128 v[188:191], v0 offset:352
	s_waitcnt lgkmcnt(6)
	v_mfma_f32_32x32x16_bf16 v[96:111], v[192:195], v[164:167], v[96:111]
	ds_read_b128 v[192:195], v0 offset:12800
	s_waitcnt lgkmcnt(6)
	v_mfma_f32_32x32x16_bf16 v[96:111], v[196:199], v[172:175], v[96:111]
	s_lshl_b32 s16, s6, 7
	s_waitcnt vmcnt(4)
	ds_write_b128 v250, v[124:127] offset:25600
	buffer_load_dwordx4 v[124:127], v232, s[24:27], s16 offen
	ds_read_b128 v[196:199], v0 offset:12832
	s_waitcnt lgkmcnt(6)
	v_mfma_f32_32x32x16_bf16 v[96:111], v[2:5], v[160:163], v[96:111]
	ds_read_b128 v[2:5], v0 offset:12864
	s_waitcnt lgkmcnt(6)
	v_mfma_f32_32x32x16_bf16 v[96:111], v[6:9], v[148:151], v[96:111]
	s_add_i32 s16, s16, 0x100000
	s_waitcnt vmcnt(4)
	ds_write_b128 v251, v[128:131] offset:25600
	buffer_load_dwordx4 v[128:131], v232, s[24:27], s16 offen
	ds_read_b128 v[6:9], v0 offset:12896
	s_waitcnt lgkmcnt(6)
	v_mfma_f32_32x32x16_bf16 v[96:111], v[10:13], v[168:171], v[96:111]
	ds_read_b128 v[10:13], v0 offset:12928
	s_waitcnt lgkmcnt(6)
	v_mfma_f32_32x32x16_bf16 v[96:111], v[184:187], v[156:159], v[96:111]
	ds_read_b128 v[184:187], v0 offset:12960
	s_waitcnt lgkmcnt(6)
	v_mfma_f32_32x32x16_bf16 v[96:111], v[188:191], v[176:179], v[96:111]
	ds_read_b128 v[188:191], v0 offset:12992
	s_waitcnt lgkmcnt(6)
	v_mfma_f32_32x32x16_bf16 v[80:95], v[192:195], v[132:135], v[80:95]
	s_nop 8
	v_exp_f32_e32 v206, v96
	v_exp_f32_e32 v207, v97
	ds_read_b128 v[192:195], v0 offset:13024
	s_waitcnt lgkmcnt(6)
	v_mfma_f32_32x32x16_bf16 v[80:95], v[196:199], v[136:139], v[80:95]
	v_add_f32_e32 v14, v207, v206
	v_add_f32_e32 v96, v182, v14
	ds_read_b128 v[196:199], v0 offset:13056
	s_waitcnt lgkmcnt(6)
	v_mfma_f32_32x32x16_bf16 v[80:95], v[2:5], v[140:143], v[80:95]
	v_exp_f32_e32 v15, v98
	v_exp_f32_e32 v183, v99
	v_exp_f32_e32 v14, v100
	v_exp_f32_e32 v182, v101
	ds_read_b128 v[2:5], v0 offset:13088
	s_waitcnt lgkmcnt(6)
	v_mfma_f32_32x32x16_bf16 v[80:95], v[6:9], v[144:147], v[80:95]
	v_add_f32_e64 v6, v182, v14
	v_add_f32_e64 v7, v183, v15
	v_add_f32_e32 v7, v7, v96
	v_add_f32_e32 v98, v6, v7
	ds_read_b128 v[6:9], v0 offset:13120
	s_waitcnt lgkmcnt(6)
	v_mfma_f32_32x32x16_bf16 v[80:95], v[10:13], v[152:155], v[80:95]
	v_exp_f32_e32 v203, v102
	v_exp_f32_e32 v205, v103
	v_exp_f32_e32 v202, v104
	v_exp_f32_e32 v204, v105
	ds_read_b128 v[10:13], v0 offset:13152
	s_waitcnt lgkmcnt(6)
	v_mfma_f32_32x32x16_bf16 v[80:95], v[184:187], v[164:167], v[80:95]
	v_add_f32_e64 v96, v204, v202
	v_add_f32_e64 v97, v205, v203
	v_add_f32_e32 v0, v97, v98
	v_add_f32_e32 v0, v96, v0
	v_add3_u32 v209, s11, v181, v229
	ds_read_b128 v[96:99], v209 offset:25600
	s_waitcnt lgkmcnt(6)
	v_mfma_f32_32x32x16_bf16 v[80:95], v[188:191], v[172:175], v[80:95]
	v_exp_f32_e32 v187, v106
	v_exp_f32_e32 v189, v107
	v_exp_f32_e32 v186, v108
	v_exp_f32_e32 v188, v109
	ds_read_b128 v[100:103], v209 offset:30208
	s_waitcnt lgkmcnt(6)
	v_mfma_f32_32x32x16_bf16 v[80:95], v[192:195], v[160:163], v[80:95]
	v_add_f32_e64 v104, v188, v186
	v_add_f32_e64 v105, v189, v187
	v_add_f32_e32 v0, v105, v0
	v_add_f32_e32 v190, v104, v0
	ds_read_b128 v[104:107], v209 offset:34816
	s_waitcnt lgkmcnt(6)
	v_mfma_f32_32x32x16_bf16 v[80:95], v[196:199], v[148:151], v[80:95]
	v_exp_f32_e32 v192, v110
	v_exp_f32_e32 v194, v111
	ds_read_b128 v[108:111], v209 offset:39424
	s_waitcnt lgkmcnt(6)
	v_mfma_f32_32x32x16_bf16 v[80:95], v[2:5], v[168:171], v[80:95]
	v_cvt_pk_bf16_f32 v2, v206, v207
	v_cvt_pk_bf16_f32 v3, v15, v183
	v_cvt_pk_bf16_f32 v4, v14, v182
	v_cvt_pk_bf16_f32 v5, v203, v205
	ds_read_b128 v[182:185], v209 offset:25632
	s_waitcnt lgkmcnt(6)
	v_mfma_f32_32x32x16_bf16 v[80:95], v[6:9], v[156:159], v[80:95]
	v_cvt_pk_bf16_f32 v6, v202, v204
	v_cvt_pk_bf16_f32 v7, v187, v189
	v_cvt_pk_bf16_f32 v8, v186, v188
	ds_read_b128 v[186:189], v209 offset:30240
	s_waitcnt lgkmcnt(6)
	v_mfma_f32_32x32x16_bf16 v[80:95], v[10:13], v[176:179], v[80:95]
	s_waitcnt lgkmcnt(5)
	v_mfma_f32_32x32x16_bf16 v[64:79], v[96:99], v[2:5], v[64:79]
	ds_read_b128 v[10:13], v209 offset:34848
	s_waitcnt lgkmcnt(5)
	v_mfma_f32_32x32x16_bf16 v[48:63], v[100:103], v[2:5], v[48:63]
	s_nop 6
	v_exp_f32_e32 v195, v80
	v_exp_f32_e32 v193, v81
	ds_read_b128 v[96:99], v209 offset:39456
	v_exp_f32_e32 v191, v82
	v_cvt_pk_bf16_f32 v9, v192, v194
	v_pk_add_f32 v[14:15], v[194:195], v[192:193]
	s_nop 0
	v_pk_add_f32 v[14:15], v[190:191], v[14:15]
	s_waitcnt lgkmcnt(5)
	v_mfma_f32_32x32x16_bf16 v[32:47], v[104:107], v[2:5], v[32:47]
	ds_read_b128 v[100:103], v209 offset:25664
	v_exp_f32_e32 v0, v83
	v_exp_f32_e32 v190, v84
	v_exp_f32_e32 v105, v85
	v_add_f32_e32 v107, v0, v190
	s_waitcnt lgkmcnt(5)
	v_mfma_f32_32x32x16_bf16 v[16:31], v[108:111], v[2:5], v[16:31]
	ds_read_b128 v[80:83], v209 offset:30272
	v_exp_f32_e32 v106, v86
	v_exp_f32_e32 v104, v87
	s_nop 0
	v_pk_add_f32 v[108:109], v[104:105], v[106:107]
	s_waitcnt lgkmcnt(5)
	v_mfma_f32_32x32x16_bf16 v[64:79], v[182:185], v[6:9], v[64:79]
	ds_read_b128 v[2:5], v209 offset:34880
	v_exp_f32_e32 v111, v88
	v_exp_f32_e32 v185, v89
	s_waitcnt lgkmcnt(5)
	v_mfma_f32_32x32x16_bf16 v[48:63], v[186:189], v[6:9], v[48:63]
	v_exp_f32_e32 v110, v90
	v_exp_f32_e32 v184, v91
	ds_read_b128 v[84:87], v209 offset:39488
	v_pk_add_f32 v[182:183], v[184:185], v[110:111]
	s_waitcnt lgkmcnt(5)
	v_mfma_f32_32x32x16_bf16 v[32:47], v[10:13], v[6:9], v[32:47]
	ds_read_b128 v[88:91], v209 offset:25696
	v_exp_f32_e32 v187, v92
	v_exp_f32_e32 v189, v93
	s_waitcnt lgkmcnt(5)
	v_mfma_f32_32x32x16_bf16 v[16:31], v[96:99], v[6:9], v[16:31]
	v_exp_f32_e32 v186, v94
	v_exp_f32_e32 v188, v95
	v_add_f32_e32 v92, v14, v15
	v_add_f32_e32 v92, v109, v92
	v_add_f32_e32 v6, v108, v92
	ds_read_b128 v[10:13], v209 offset:30304
	v_add_f32_e32 v6, v183, v6
	v_pk_add_f32 v[14:15], v[188:189], v[186:187]
	v_add_f32_e32 v6, v182, v6
	v_add_f32_e32 v6, v15, v6
	v_add_f32_e32 v182, v14, v6
	v_cvt_pk_bf16_f32 v6, v195, v193
	v_cvt_pk_bf16_f32 v7, v191, v0
	v_cvt_pk_bf16_f32 v8, v190, v105
	v_cvt_pk_bf16_f32 v9, v106, v104
	v_cvt_pk_bf16_f32 v92, v111, v185
	v_cvt_pk_bf16_f32 v93, v110, v184
	v_cvt_pk_bf16_f32 v94, v187, v189
	v_cvt_pk_bf16_f32 v95, v186, v188
	s_waitcnt lgkmcnt(5)
	v_mfma_f32_32x32x16_bf16 v[64:79], v[100:103], v[6:9], v[64:79]
	ds_read_b128 v[96:99], v209 offset:34912
	s_waitcnt lgkmcnt(5)
	v_mfma_f32_32x32x16_bf16 v[48:63], v[80:83], v[6:9], v[48:63]
	ds_read_b128 v[100:103], v209 offset:39520
	s_waitcnt lgkmcnt(5)
	v_mfma_f32_32x32x16_bf16 v[32:47], v[2:5], v[6:9], v[32:47]
	s_waitcnt lgkmcnt(4)
	v_mfma_f32_32x32x16_bf16 v[16:31], v[84:87], v[6:9], v[16:31]
	s_waitcnt lgkmcnt(3)
	v_mfma_f32_32x32x16_bf16 v[64:79], v[88:91], v[92:95], v[64:79]
	s_waitcnt lgkmcnt(2)
	v_mfma_f32_32x32x16_bf16 v[48:63], v[10:13], v[92:95], v[48:63]
	s_waitcnt lgkmcnt(1)
	v_mfma_f32_32x32x16_bf16 v[32:47], v[96:99], v[92:95], v[32:47]
	s_waitcnt lgkmcnt(0)
	v_mfma_f32_32x32x16_bf16 v[16:31], v[100:103], v[92:95], v[16:31]

.Lattn1_stage_only:
	s_mul_i32 s16, s6, 0x6000
	s_waitcnt vmcnt(4)
	ds_write_b128 v247, v[112:115]
	buffer_load_dwordx4 v[112:115], v230, s[20:23], s16 offen
	s_add_i32 s17, s16, 0x2000
	s_waitcnt vmcnt(4)
	ds_write_b128 v248, v[116:119]
	buffer_load_dwordx4 v[116:119], v230, s[20:23], s17 offen
	s_addk_i32 s16, 0x4000
	s_waitcnt vmcnt(4)
	ds_write_b128 v249, v[120:123]
	buffer_load_dwordx4 v[120:123], v230, s[20:23], s16 offen
	s_lshl_b32 s16, s6, 7
	s_waitcnt vmcnt(4)
	ds_write_b128 v250, v[124:127] offset:25600
	buffer_load_dwordx4 v[124:127], v232, s[24:27], s16 offen
	s_add_i32 s16, s16, 0x100000
	s_waitcnt vmcnt(4)
	ds_write_b128 v251, v[128:131] offset:25600
	buffer_load_dwordx4 v[128:131], v232, s[24:27], s16 offen
	s_branch .LBB0_633

.LBB0_643:
	v_mul_f32_e32 v76, v51, v51
	v_fmac_f32_e32 v76, v50, v50
	v_fmac_f32_e32 v76, v52, v52
	v_fmac_f32_e32 v76, v53, v53
	v_fmac_f32_e32 v76, v54, v54
	v_fmac_f32_e32 v76, v55, v55
	v_fmac_f32_e32 v76, v56, v56
	v_fmac_f32_e32 v76, v57, v57
	v_fmac_f32_e32 v76, v58, v58
	v_fmac_f32_e32 v76, v59, v59
	v_fmac_f32_e32 v76, v60, v60
	v_fmac_f32_e32 v76, v61, v61
	v_fmac_f32_e32 v76, v62, v62
	v_fmac_f32_e32 v76, v63, v63
	v_fmac_f32_e32 v76, v64, v64
	v_fmac_f32_e32 v76, v65, v65
	v_fmac_f32_e32 v76, v34, v34
	v_fmac_f32_e32 v76, v35, v35
	v_fmac_f32_e32 v76, v36, v36
	v_fmac_f32_e32 v76, v37, v37
	v_fmac_f32_e32 v76, v38, v38
	v_fmac_f32_e32 v76, v39, v39
	v_fmac_f32_e32 v76, v40, v40
	v_fmac_f32_e32 v76, v41, v41
	v_fmac_f32_e32 v76, v42, v42
	v_fmac_f32_e32 v76, v43, v43
	v_fmac_f32_e32 v76, v44, v44
	v_fmac_f32_e32 v76, v45, v45
	v_fmac_f32_e32 v76, v46, v46
	v_fmac_f32_e32 v76, v47, v47
	v_fmac_f32_e32 v76, v48, v48
	v_fmac_f32_e32 v76, v49, v49
	v_fmac_f32_e32 v76, v18, v18
	v_fmac_f32_e32 v76, v19, v19
	v_fmac_f32_e32 v76, v20, v20
	v_fmac_f32_e32 v76, v21, v21
	v_fmac_f32_e32 v76, v22, v22
	v_fmac_f32_e32 v76, v23, v23
	v_fmac_f32_e32 v76, v24, v24
	v_fmac_f32_e32 v76, v25, v25
	v_fmac_f32_e32 v76, v26, v26
	v_fmac_f32_e32 v76, v27, v27
	v_fmac_f32_e32 v76, v28, v28
	v_fmac_f32_e32 v76, v29, v29
	v_fmac_f32_e32 v76, v30, v30
	v_fmac_f32_e32 v76, v31, v31
	v_fmac_f32_e32 v76, v32, v32
	v_fmac_f32_e32 v76, v33, v33
	v_fmac_f32_e32 v76, v2, v2
	v_fmac_f32_e32 v76, v3, v3
	v_fmac_f32_e32 v76, v4, v4
	v_fmac_f32_e32 v76, v5, v5
	v_fmac_f32_e32 v76, v6, v6
	v_fmac_f32_e32 v76, v7, v7
	v_pk_mul_f32 v[74:75], v[8:9], v[8:9]
	v_pk_mul_f32 v[72:73], v[10:11], v[10:11]
	v_add_f32_e32 v74, v74, v76
	v_add_f32_e32 v74, v75, v74
	v_add_f32_e32 v72, v72, v74
	v_pk_mul_f32 v[70:71], v[12:13], v[12:13]
	v_add_f32_e32 v72, v73, v72
	v_add_f32_e32 v70, v70, v72
	v_pk_mul_f32 v[68:69], v[14:15], v[14:15]
	v_add_f32_e32 v70, v71, v70
	v_add_f32_e32 v68, v68, v70
	v_pk_mul_f32 v[66:67], v[16:17], v[16:17]
	v_add_f32_e32 v68, v69, v68
	v_add_f32_e32 v66, v66, v68
	v_add_f32_e32 v66, v67, v66
	ds_bpermute_b32 v67, v212, v66
	s_xor_b64 s[54:55], s[4:5], -1
	s_lshl_b32 s4, s59, 5
	s_or_b32 s68, s4, s16
	s_ashr_i32 s69, s68, 31
	s_mul_i32 s5, s68, 0x2880
	v_readlane_b32 s6, v246, 36
	s_waitcnt lgkmcnt(0)
	v_add_f32_e32 v66, v66, v67
	s_mul_hi_i32 s4, s68, 0x2880
	v_readlane_b32 s7, v246, 37
	s_add_u32 s5, s6, s5
	v_fmamk_f32 v66, v66, 0x3c000000, v216
	s_addc_u32 s6, s7, s4
	v_cmp_gt_f32_e32 vcc, s36, v66
	v_mul_f32_e32 v67, 0x4b800000, v66
	s_add_u32 s4, s5, s58
	v_cndmask_b32_e32 v66, v66, v67, vcc
	s_addc_u32 s5, s6, 0
	v_rsq_f32_e32 v78, v66
	v_lshl_add_u64 v[66:67], s[4:5], 0, v[0:1]
	s_mov_b64 s[4:5], 0x1800
	v_lshl_add_u64 v[76:77], v[66:67], 0, s[4:5]
	v_mov_b32_e32 v179, v1
	v_lshl_add_u64 v[66:67], v[76:77], 0, v[178:179]
	global_load_dwordx4 v[100:103], v[66:67], off nt
	v_mov_b32_e32 v181, v1
	v_lshl_add_u64 v[70:71], v[76:77], 0, v[180:181]
	global_load_dwordx4 v[104:107], v[70:71], off nt
	v_add_co_u32_e64 v66, s[4:5], s37, v70
	v_mov_b32_e32 v183, v1
	v_mov_b32_e32 v185, v1
	v_addc_co_u32_e64 v67, s[4:5], 0, v71, s[4:5]
	global_load_dwordx4 v[108:111], v[66:67], off offset:512 nt
	s_mov_b32 s4, 0x14000
	v_add_co_u32_e64 v66, s[4:5], s4, v70
	v_mov_b32_e32 v187, v1
	v_mov_b32_e32 v189, v1
	v_addc_co_u32_e64 v67, s[4:5], 0, v71, s[4:5]
	global_load_dwordx4 v[112:115], v[66:67], off offset:1024 nt
	v_lshl_add_u64 v[68:69], v[76:77], 0, v[182:183]
	global_load_dwordx4 v[116:119], v[68:69], off nt
	v_lshl_add_u64 v[68:69], v[76:77], 0, v[184:185]
	global_load_dwordx4 v[120:123], v[68:69], off nt
	v_lshl_add_u64 v[68:69], v[76:77], 0, v[186:187]
	global_load_dwordx4 v[124:127], v[68:69], off nt
	v_lshl_add_u64 v[68:69], v[76:77], 0, v[188:189]
	global_load_dwordx4 v[128:131], v[68:69], off nt
	global_load_dwordx4 v[72:75], v[176:177], off
	v_add_u32_e32 v82, v208, v207
	v_mul_f32_e32 v79, 0x45800000, v78
	v_mov_b32_e32 v191, v1
	v_mov_b32_e32 v193, v1
	v_mov_b32_e32 v195, v1
	v_mov_b32_e32 v197, v1
	v_mov_b32_e32 v199, v1
	v_mov_b32_e32 v201, v1
	v_mov_b32_e32 v203, v1
	v_mov_b32_e32 v205, v1
	s_mov_b32 s59, 1
	v_add_u32_e32 v67, 0x840, v229
	v_cndmask_b32_e32 v66, v78, v79, vcc
	v_pk_mul_f32 v[50:51], v[50:51], v[66:67] op_sel_hi:[1,0]
	v_pk_mul_f32 v[52:53], v[52:53], v[66:67] op_sel_hi:[1,0]
	v_pk_mul_f32 v[54:55], v[54:55], v[66:67] op_sel_hi:[1,0]
	v_pk_mul_f32 v[56:57], v[56:57], v[66:67] op_sel_hi:[1,0]
	v_pk_mul_f32 v[58:59], v[58:59], v[66:67] op_sel_hi:[1,0]
	v_pk_mul_f32 v[34:35], v[34:35], v[66:67] op_sel_hi:[1,0]
	v_pk_mul_f32 v[36:37], v[36:37], v[66:67] op_sel_hi:[1,0]
	v_pk_mul_f32 v[38:39], v[38:39], v[66:67] op_sel_hi:[1,0]
	v_pk_mul_f32 v[40:41], v[40:41], v[66:67] op_sel_hi:[1,0]
	v_pk_mul_f32 v[42:43], v[42:43], v[66:67] op_sel_hi:[1,0]
	v_pk_mul_f32 v[18:19], v[18:19], v[66:67] op_sel_hi:[1,0]
	v_pk_mul_f32 v[20:21], v[20:21], v[66:67] op_sel_hi:[1,0]
	v_pk_mul_f32 v[22:23], v[22:23], v[66:67] op_sel_hi:[1,0]
	v_pk_mul_f32 v[24:25], v[24:25], v[66:67] op_sel_hi:[1,0]
	v_pk_mul_f32 v[26:27], v[26:27], v[66:67] op_sel_hi:[1,0]
	v_pk_mul_f32 v[2:3], v[2:3], v[66:67] op_sel_hi:[1,0]
	v_pk_mul_f32 v[4:5], v[4:5], v[66:67] op_sel_hi:[1,0]
	v_pk_mul_f32 v[6:7], v[6:7], v[66:67] op_sel_hi:[1,0]
	v_pk_mul_f32 v[8:9], v[8:9], v[66:67] op_sel_hi:[1,0]
	v_pk_mul_f32 v[10:11], v[10:11], v[66:67] op_sel_hi:[1,0]
	s_lshl_b64 s[4:5], s[68:69], 12
	s_mov_b64 s[68:69], -1
	s_andn2_b64 vcc, exec, s[54:55]
	v_add_u32_e32 v68, 0xc60, v229
	v_add_u32_e32 v69, 0x18c0, v229
	v_add_u32_e32 v70, 0x1080, v229
	v_add_u32_e32 v71, 0x14a0, v229
	s_waitcnt vmcnt(8)
	ds_write2_b64 v228, v[100:101], v[102:103] offset1:1
	s_waitcnt vmcnt(7)
	ds_write2_b64 v229, v[104:105], v[106:107] offset1:1
	s_waitcnt vmcnt(6)
	ds_write2_b64 v229, v[108:109], v[110:111] offset0:132 offset1:133
	s_waitcnt vmcnt(5)
	ds_write2_b64 v67, v[112:113], v[114:115] offset1:1
	s_waitcnt vmcnt(4)
	ds_write2_b64 v68, v[116:117], v[118:119] offset1:1
	s_waitcnt vmcnt(3)
	ds_write2_b64 v70, v[120:121], v[122:123] offset1:1
	s_waitcnt vmcnt(2)
	ds_write2_b64 v71, v[124:125], v[126:127] offset1:1
	s_waitcnt vmcnt(1)
	ds_write2_b64 v69, v[128:129], v[130:131] offset1:1
	ds_read_b64 v[76:77], v82
	s_waitcnt lgkmcnt(0)
	v_lshlrev_b32_e32 v78, 16, v76
	v_and_b32_e32 v79, 0xffff0000, v76
	v_mul_f32_e32 v76, 0xbfb8aa3b, v78
	v_exp_f32_e32 v76, v76
	s_waitcnt vmcnt(0)
	v_pk_mul_f32 v[50:51], v[72:73], v[50:51]
	v_mul_f32_e32 v72, 0xbfb8aa3b, v79
	v_exp_f32_e32 v72, v72
	v_add_f32_e32 v76, 1.0, v76
	v_rcp_f32_e32 v80, v76
	v_pk_mul_f32 v[52:53], v[74:75], v[52:53]
	v_add_f32_e32 v72, 1.0, v72
	v_rcp_f32_e32 v81, v72
	s_nop 0
	v_pk_mul_f32 v[72:73], v[80:81], v[78:79]
	s_nop 0
	v_pk_mul_f32 v[50:51], v[72:73], v[50:51]
	v_lshlrev_b32_e32 v72, 16, v77
	v_and_b32_e32 v73, 0xffff0000, v77
	v_mul_f32_e32 v76, 0xbfb8aa3b, v72
	v_mul_f32_e32 v74, 0xbfb8aa3b, v73
	v_exp_f32_e32 v76, v76
	v_exp_f32_e32 v74, v74
	v_cvt_pk_bf16_f32 v50, v50, v51
	v_add_u32_e32 v78, v208, v227
	v_add_f32_e32 v76, 1.0, v76
	v_add_f32_e32 v74, 1.0, v74
	v_rcp_f32_e32 v76, v76
	v_rcp_f32_e32 v77, v74
	s_nop 0
	v_pk_mul_f32 v[72:73], v[76:77], v[72:73]
	s_nop 0
	v_pk_mul_f32 v[52:53], v[72:73], v[52:53]
	global_load_dwordx4 v[72:75], v[176:177], off offset:32
	v_cvt_pk_bf16_f32 v51, v52, v53
	ds_write_b64 v82, v[50:51]
	ds_read_b64 v[50:51], v78
	s_waitcnt lgkmcnt(0)
	v_lshlrev_b32_e32 v52, 16, v50
	v_and_b32_e32 v53, 0xffff0000, v50
	v_mul_f32_e32 v50, 0xbfb8aa3b, v52
	v_exp_f32_e32 v50, v50
	s_waitcnt vmcnt(0)
	v_pk_mul_f32 v[54:55], v[72:73], v[54:55]
	v_add_f32_e32 v50, 1.0, v50
	v_rcp_f32_e32 v76, v50
	v_mul_f32_e32 v50, 0xbfb8aa3b, v53
	v_exp_f32_e32 v50, v50
	v_pk_mul_f32 v[56:57], v[74:75], v[56:57]
	v_add_f32_e32 v50, 1.0, v50
	v_rcp_f32_e32 v77, v50
	v_lshlrev_b32_e32 v50, 16, v51
	v_and_b32_e32 v51, 0xffff0000, v51
	v_pk_mul_f32 v[52:53], v[76:77], v[52:53]
	s_nop 0
	v_pk_mul_f32 v[52:53], v[52:53], v[54:55]
	v_mul_f32_e32 v54, 0xbfb8aa3b, v50
	v_mul_f32_e32 v55, 0xbfb8aa3b, v51
	v_exp_f32_e32 v54, v54
	v_exp_f32_e32 v55, v55
	v_cvt_pk_bf16_f32 v52, v52, v53
	v_add_f32_e32 v54, 1.0, v54
	v_add_f32_e32 v55, 1.0, v55
	v_rcp_f32_e32 v54, v54
	v_rcp_f32_e32 v55, v55
	s_nop 0
	v_pk_mul_f32 v[50:51], v[54:55], v[50:51]
	s_nop 0
	v_pk_mul_f32 v[50:51], v[50:51], v[56:57]
	s_nop 0
	v_cvt_pk_bf16_f32 v53, v50, v51
	ds_write_b64 v78, v[52:53]
	global_load_dwordx4 v[52:55], v[176:177], off offset:64
	ds_read_b64 v[50:51], v230
	s_waitcnt lgkmcnt(0)
	v_lshlrev_b32_e32 v56, 16, v50
	v_and_b32_e32 v57, 0xffff0000, v50
	v_mul_f32_e32 v50, 0xbfb8aa3b, v56
	v_exp_f32_e32 v50, v50
	s_waitcnt vmcnt(0)
	v_pk_mul_f32 v[52:53], v[52:53], v[58:59]
	v_add_f32_e32 v50, 1.0, v50
	v_rcp_f32_e32 v72, v50
	v_mul_f32_e32 v50, 0xbfb8aa3b, v57
	v_exp_f32_e32 v50, v50
	v_pk_mul_f32 v[58:59], v[60:61], v[66:67] op_sel_hi:[1,0]
	v_pk_mul_f32 v[60:61], v[62:63], v[66:67] op_sel_hi:[1,0]
	v_pk_mul_f32 v[54:55], v[54:55], v[58:59]
	v_add_f32_e32 v50, 1.0, v50
	v_rcp_f32_e32 v73, v50
	v_lshlrev_b32_e32 v50, 16, v51
	v_and_b32_e32 v51, 0xffff0000, v51
	v_pk_mul_f32 v[56:57], v[72:73], v[56:57]
	s_nop 0
	v_pk_mul_f32 v[52:53], v[56:57], v[52:53]
	v_mul_f32_e32 v56, 0xbfb8aa3b, v50
	v_mul_f32_e32 v57, 0xbfb8aa3b, v51
	v_exp_f32_e32 v56, v56
	v_exp_f32_e32 v57, v57
	v_cvt_pk_bf16_f32 v52, v52, v53
	v_add_f32_e32 v56, 1.0, v56
	v_add_f32_e32 v57, 1.0, v57
	v_rcp_f32_e32 v56, v56
	v_rcp_f32_e32 v57, v57
	s_nop 0
	v_pk_mul_f32 v[50:51], v[56:57], v[50:51]
	s_nop 0
	v_pk_mul_f32 v[50:51], v[50:51], v[54:55]
	ds_read_b64 v[54:55], v231
	v_cvt_pk_bf16_f32 v53, v50, v51
	ds_write_b64 v230, v[52:53]
	global_load_dwordx4 v[50:53], v[176:177], off offset:96
	s_waitcnt lgkmcnt(1)
	v_lshlrev_b32_e32 v56, 16, v54
	v_and_b32_e32 v57, 0xffff0000, v54
	v_mul_f32_e32 v54, 0xbfb8aa3b, v56
	v_exp_f32_e32 v54, v54
	s_waitcnt vmcnt(0)
	v_pk_mul_f32 v[50:51], v[50:51], v[60:61]
	v_add_f32_e32 v54, 1.0, v54
	v_rcp_f32_e32 v58, v54
	v_mul_f32_e32 v54, 0xbfb8aa3b, v57
	v_exp_f32_e32 v54, v54
	s_nop 0
	v_add_f32_e32 v54, 1.0, v54
	v_rcp_f32_e32 v59, v54
	v_lshlrev_b32_e32 v54, 16, v55
	v_and_b32_e32 v55, 0xffff0000, v55
	v_pk_mul_f32 v[56:57], v[58:59], v[56:57]
	s_nop 0
	v_pk_mul_f32 v[50:51], v[56:57], v[50:51]
	v_mul_f32_e32 v56, 0xbfb8aa3b, v54
	v_mul_f32_e32 v57, 0xbfb8aa3b, v55
	v_exp_f32_e32 v56, v56
	v_exp_f32_e32 v57, v57
	v_pk_mul_f32 v[58:59], v[64:65], v[66:67] op_sel_hi:[1,0]
	v_cvt_pk_bf16_f32 v50, v50, v51
	v_add_f32_e32 v56, 1.0, v56
	v_add_f32_e32 v57, 1.0, v57
	v_rcp_f32_e32 v56, v56
	v_rcp_f32_e32 v57, v57
	v_pk_mul_f32 v[52:53], v[52:53], v[58:59]
	v_pk_mul_f32 v[54:55], v[56:57], v[54:55]
	s_nop 0
	v_pk_mul_f32 v[52:53], v[54:55], v[52:53]
	s_nop 0
	v_cvt_pk_bf16_f32 v51, v52, v53
	global_load_dwordx4 v[52:55], v[176:177], off offset:128
	ds_write_b64 v231, v[50:51]
	ds_read_b64 v[50:51], v232
	s_waitcnt lgkmcnt(0)
	v_lshlrev_b32_e32 v56, 16, v50
	v_and_b32_e32 v57, 0xffff0000, v50
	v_mul_f32_e32 v50, 0xbfb8aa3b, v56
	v_exp_f32_e32 v50, v50
	s_waitcnt vmcnt(0)
	v_pk_mul_f32 v[34:35], v[52:53], v[34:35]
	v_add_f32_e32 v50, 1.0, v50
	v_rcp_f32_e32 v58, v50
	v_mul_f32_e32 v50, 0xbfb8aa3b, v57
	v_exp_f32_e32 v50, v50
	v_pk_mul_f32 v[36:37], v[54:55], v[36:37]
	v_add_f32_e32 v50, 1.0, v50
	v_rcp_f32_e32 v59, v50
	v_lshlrev_b32_e32 v50, 16, v51
	v_and_b32_e32 v51, 0xffff0000, v51
	v_pk_mul_f32 v[52:53], v[58:59], v[56:57]
	s_nop 0
	v_pk_mul_f32 v[34:35], v[52:53], v[34:35]
	v_mul_f32_e32 v52, 0xbfb8aa3b, v50
	v_mul_f32_e32 v53, 0xbfb8aa3b, v51
	v_exp_f32_e32 v52, v52
	v_exp_f32_e32 v53, v53
	v_cvt_pk_bf16_f32 v34, v34, v35
	v_add_f32_e32 v52, 1.0, v52
	v_add_f32_e32 v53, 1.0, v53
	v_rcp_f32_e32 v52, v52
	v_rcp_f32_e32 v53, v53
	s_nop 0
	v_pk_mul_f32 v[50:51], v[52:53], v[50:51]
	s_nop 0
	v_pk_mul_f32 v[36:37], v[50:51], v[36:37]
	global_load_dwordx4 v[50:53], v[176:177], off offset:160
	v_cvt_pk_bf16_f32 v35, v36, v37
	ds_write_b64 v232, v[34:35]
	ds_read_b64 v[34:35], v233
	s_waitcnt lgkmcnt(0)
	v_lshlrev_b32_e32 v36, 16, v34
	v_and_b32_e32 v37, 0xffff0000, v34
	v_mul_f32_e32 v34, 0xbfb8aa3b, v36
	v_exp_f32_e32 v34, v34
	s_waitcnt vmcnt(0)
	v_pk_mul_f32 v[38:39], v[50:51], v[38:39]
	v_add_f32_e32 v34, 1.0, v34
	v_rcp_f32_e32 v54, v34
	v_mul_f32_e32 v34, 0xbfb8aa3b, v37
	v_exp_f32_e32 v34, v34
	v_pk_mul_f32 v[40:41], v[52:53], v[40:41]
	v_add_f32_e32 v34, 1.0, v34
	v_rcp_f32_e32 v55, v34
	v_lshlrev_b32_e32 v34, 16, v35
	v_and_b32_e32 v35, 0xffff0000, v35
	v_pk_mul_f32 v[36:37], v[54:55], v[36:37]
	s_nop 0
	v_pk_mul_f32 v[36:37], v[36:37], v[38:39]
	v_mul_f32_e32 v38, 0xbfb8aa3b, v34
	v_mul_f32_e32 v39, 0xbfb8aa3b, v35
	v_exp_f32_e32 v38, v38
	v_exp_f32_e32 v39, v39
	v_cvt_pk_bf16_f32 v36, v36, v37
	v_add_f32_e32 v38, 1.0, v38
	v_add_f32_e32 v39, 1.0, v39
	v_rcp_f32_e32 v38, v38
	v_rcp_f32_e32 v39, v39
	s_nop 0
	v_pk_mul_f32 v[34:35], v[38:39], v[34:35]
	s_nop 0
	v_pk_mul_f32 v[34:35], v[34:35], v[40:41]
	s_nop 0
	v_cvt_pk_bf16_f32 v37, v34, v35
	ds_write_b64 v233, v[36:37]
	global_load_dwordx4 v[36:39], v[176:177], off offset:192
	ds_read_b64 v[34:35], v234
	s_waitcnt lgkmcnt(0)
	v_lshlrev_b32_e32 v40, 16, v34
	v_and_b32_e32 v41, 0xffff0000, v34
	v_mul_f32_e32 v34, 0xbfb8aa3b, v40
	v_exp_f32_e32 v34, v34
	s_waitcnt vmcnt(0)
	v_pk_mul_f32 v[36:37], v[36:37], v[42:43]
	v_add_f32_e32 v34, 1.0, v34
	v_rcp_f32_e32 v50, v34
	v_mul_f32_e32 v34, 0xbfb8aa3b, v41
	v_exp_f32_e32 v34, v34
	v_pk_mul_f32 v[42:43], v[44:45], v[66:67] op_sel_hi:[1,0]
	v_pk_mul_f32 v[44:45], v[46:47], v[66:67] op_sel_hi:[1,0]
	v_pk_mul_f32 v[38:39], v[38:39], v[42:43]
	v_add_f32_e32 v34, 1.0, v34
	v_rcp_f32_e32 v51, v34
	v_lshlrev_b32_e32 v34, 16, v35
	v_and_b32_e32 v35, 0xffff0000, v35
	v_pk_mul_f32 v[40:41], v[50:51], v[40:41]
	s_nop 0
	v_pk_mul_f32 v[36:37], v[40:41], v[36:37]
	v_mul_f32_e32 v40, 0xbfb8aa3b, v34
	v_mul_f32_e32 v41, 0xbfb8aa3b, v35
	v_exp_f32_e32 v40, v40
	v_exp_f32_e32 v41, v41
	v_cvt_pk_bf16_f32 v36, v36, v37
	v_add_f32_e32 v40, 1.0, v40
	v_add_f32_e32 v41, 1.0, v41
	v_rcp_f32_e32 v40, v40
	v_rcp_f32_e32 v41, v41
	s_nop 0
	v_pk_mul_f32 v[34:35], v[40:41], v[34:35]
	s_nop 0
	v_pk_mul_f32 v[34:35], v[34:35], v[38:39]
	ds_read_b64 v[38:39], v235
	v_cvt_pk_bf16_f32 v37, v34, v35
	ds_write_b64 v234, v[36:37]
	global_load_dwordx4 v[34:37], v[176:177], off offset:224
	s_waitcnt lgkmcnt(1)
	v_lshlrev_b32_e32 v40, 16, v38
	v_and_b32_e32 v41, 0xffff0000, v38
	v_mul_f32_e32 v38, 0xbfb8aa3b, v40
	v_exp_f32_e32 v38, v38
	s_waitcnt vmcnt(0)
	v_pk_mul_f32 v[34:35], v[34:35], v[44:45]
	v_add_f32_e32 v38, 1.0, v38
	v_rcp_f32_e32 v42, v38
	v_mul_f32_e32 v38, 0xbfb8aa3b, v41
	v_exp_f32_e32 v38, v38
	s_nop 0
	v_add_f32_e32 v38, 1.0, v38
	v_rcp_f32_e32 v43, v38
	v_lshlrev_b32_e32 v38, 16, v39
	v_and_b32_e32 v39, 0xffff0000, v39
	v_pk_mul_f32 v[40:41], v[42:43], v[40:41]
	s_nop 0
	v_pk_mul_f32 v[34:35], v[40:41], v[34:35]
	v_mul_f32_e32 v40, 0xbfb8aa3b, v38
	v_mul_f32_e32 v41, 0xbfb8aa3b, v39
	v_exp_f32_e32 v40, v40
	v_exp_f32_e32 v41, v41
	v_pk_mul_f32 v[42:43], v[48:49], v[66:67] op_sel_hi:[1,0]
	v_cvt_pk_bf16_f32 v34, v34, v35
	v_add_f32_e32 v40, 1.0, v40
	v_add_f32_e32 v41, 1.0, v41
	v_rcp_f32_e32 v40, v40
	v_rcp_f32_e32 v41, v41
	v_pk_mul_f32 v[36:37], v[36:37], v[42:43]
	v_pk_mul_f32 v[38:39], v[40:41], v[38:39]
	s_nop 0
	v_pk_mul_f32 v[36:37], v[38:39], v[36:37]
	s_nop 0
	v_cvt_pk_bf16_f32 v35, v36, v37
	global_load_dwordx4 v[36:39], v[176:177], off offset:256
	ds_write_b64 v235, v[34:35]
	ds_read_b64 v[34:35], v236
	s_waitcnt lgkmcnt(0)
	v_lshlrev_b32_e32 v40, 16, v34
	v_and_b32_e32 v41, 0xffff0000, v34
	v_mul_f32_e32 v34, 0xbfb8aa3b, v40
	v_exp_f32_e32 v34, v34
	s_waitcnt vmcnt(0)
	v_pk_mul_f32 v[18:19], v[36:37], v[18:19]
	v_add_f32_e32 v34, 1.0, v34
	v_rcp_f32_e32 v42, v34
	v_mul_f32_e32 v34, 0xbfb8aa3b, v41
	v_exp_f32_e32 v34, v34
	v_pk_mul_f32 v[20:21], v[38:39], v[20:21]
	v_add_f32_e32 v34, 1.0, v34
	v_rcp_f32_e32 v43, v34
	v_lshlrev_b32_e32 v34, 16, v35
	v_and_b32_e32 v35, 0xffff0000, v35
	v_pk_mul_f32 v[36:37], v[42:43], v[40:41]
	s_nop 0
	v_pk_mul_f32 v[18:19], v[36:37], v[18:19]
	v_mul_f32_e32 v36, 0xbfb8aa3b, v34
	v_mul_f32_e32 v37, 0xbfb8aa3b, v35
	v_exp_f32_e32 v36, v36
	v_exp_f32_e32 v37, v37
	v_cvt_pk_bf16_f32 v18, v18, v19
	v_add_f32_e32 v36, 1.0, v36
	v_add_f32_e32 v37, 1.0, v37
	v_rcp_f32_e32 v36, v36
	v_rcp_f32_e32 v37, v37
	s_nop 0
	v_pk_mul_f32 v[34:35], v[36:37], v[34:35]
	s_nop 0
	v_pk_mul_f32 v[20:21], v[34:35], v[20:21]
	global_load_dwordx4 v[34:37], v[176:177], off offset:288
	v_cvt_pk_bf16_f32 v19, v20, v21
	ds_write_b64 v236, v[18:19]
	ds_read_b64 v[18:19], v237
	s_waitcnt lgkmcnt(0)
	v_lshlrev_b32_e32 v20, 16, v18
	v_and_b32_e32 v21, 0xffff0000, v18
	v_mul_f32_e32 v18, 0xbfb8aa3b, v20
	v_exp_f32_e32 v18, v18
	s_waitcnt vmcnt(0)
	v_pk_mul_f32 v[22:23], v[34:35], v[22:23]
	v_add_f32_e32 v18, 1.0, v18
	v_rcp_f32_e32 v38, v18
	v_mul_f32_e32 v18, 0xbfb8aa3b, v21
	v_exp_f32_e32 v18, v18
	v_pk_mul_f32 v[24:25], v[36:37], v[24:25]
	v_add_f32_e32 v18, 1.0, v18
	v_rcp_f32_e32 v39, v18
	v_lshlrev_b32_e32 v18, 16, v19
	v_and_b32_e32 v19, 0xffff0000, v19
	v_pk_mul_f32 v[20:21], v[38:39], v[20:21]
	s_nop 0
	v_pk_mul_f32 v[20:21], v[20:21], v[22:23]
	v_mul_f32_e32 v22, 0xbfb8aa3b, v18
	v_mul_f32_e32 v23, 0xbfb8aa3b, v19
	v_exp_f32_e32 v22, v22
	v_exp_f32_e32 v23, v23
	v_cvt_pk_bf16_f32 v20, v20, v21
	v_add_f32_e32 v22, 1.0, v22
	v_add_f32_e32 v23, 1.0, v23
	v_rcp_f32_e32 v22, v22
	v_rcp_f32_e32 v23, v23
	s_nop 0
	v_pk_mul_f32 v[18:19], v[22:23], v[18:19]
	s_nop 0
	v_pk_mul_f32 v[18:19], v[18:19], v[24:25]
	s_nop 0
	v_cvt_pk_bf16_f32 v21, v18, v19
	ds_write_b64 v237, v[20:21]
	global_load_dwordx4 v[20:23], v[176:177], off offset:320
	ds_read_b64 v[18:19], v238
	s_waitcnt lgkmcnt(0)
	v_lshlrev_b32_e32 v24, 16, v18
	v_and_b32_e32 v25, 0xffff0000, v18
	v_mul_f32_e32 v18, 0xbfb8aa3b, v24
	v_exp_f32_e32 v18, v18
	s_waitcnt vmcnt(0)
	v_pk_mul_f32 v[20:21], v[20:21], v[26:27]
	v_add_f32_e32 v18, 1.0, v18
	v_rcp_f32_e32 v34, v18
	v_mul_f32_e32 v18, 0xbfb8aa3b, v25
	v_exp_f32_e32 v18, v18
	v_pk_mul_f32 v[26:27], v[28:29], v[66:67] op_sel_hi:[1,0]
	v_pk_mul_f32 v[28:29], v[30:31], v[66:67] op_sel_hi:[1,0]
	v_pk_mul_f32 v[22:23], v[22:23], v[26:27]
	v_add_f32_e32 v18, 1.0, v18
	v_rcp_f32_e32 v35, v18
	v_lshlrev_b32_e32 v18, 16, v19
	v_and_b32_e32 v19, 0xffff0000, v19
	v_pk_mul_f32 v[24:25], v[34:35], v[24:25]
	s_nop 0
	v_pk_mul_f32 v[20:21], v[24:25], v[20:21]
	v_mul_f32_e32 v24, 0xbfb8aa3b, v18
	v_mul_f32_e32 v25, 0xbfb8aa3b, v19
	v_exp_f32_e32 v24, v24
	v_exp_f32_e32 v25, v25
	v_cvt_pk_bf16_f32 v20, v20, v21
	v_add_f32_e32 v24, 1.0, v24
	v_add_f32_e32 v25, 1.0, v25
	v_rcp_f32_e32 v24, v24
	v_rcp_f32_e32 v25, v25
	s_nop 0
	v_pk_mul_f32 v[18:19], v[24:25], v[18:19]
	s_nop 0
	v_pk_mul_f32 v[18:19], v[18:19], v[22:23]
	ds_read_b64 v[22:23], v239
	v_cvt_pk_bf16_f32 v21, v18, v19
	ds_write_b64 v238, v[20:21]
	global_load_dwordx4 v[18:21], v[176:177], off offset:352
	s_waitcnt lgkmcnt(1)
	v_lshlrev_b32_e32 v24, 16, v22
	v_and_b32_e32 v25, 0xffff0000, v22
	v_mul_f32_e32 v22, 0xbfb8aa3b, v24
	v_exp_f32_e32 v22, v22
	s_waitcnt vmcnt(0)
	v_pk_mul_f32 v[18:19], v[18:19], v[28:29]
	v_add_f32_e32 v22, 1.0, v22
	v_rcp_f32_e32 v26, v22
	v_mul_f32_e32 v22, 0xbfb8aa3b, v25
	v_exp_f32_e32 v22, v22
	s_nop 0
	v_add_f32_e32 v22, 1.0, v22
	v_rcp_f32_e32 v27, v22
	v_lshlrev_b32_e32 v22, 16, v23
	v_and_b32_e32 v23, 0xffff0000, v23
	v_pk_mul_f32 v[24:25], v[26:27], v[24:25]
	s_nop 0
	v_pk_mul_f32 v[18:19], v[24:25], v[18:19]
	v_mul_f32_e32 v24, 0xbfb8aa3b, v22
	v_mul_f32_e32 v25, 0xbfb8aa3b, v23
	v_exp_f32_e32 v24, v24
	v_exp_f32_e32 v25, v25
	v_pk_mul_f32 v[26:27], v[32:33], v[66:67] op_sel_hi:[1,0]
	v_cvt_pk_bf16_f32 v18, v18, v19
	v_add_f32_e32 v24, 1.0, v24
	v_add_f32_e32 v25, 1.0, v25
	v_rcp_f32_e32 v24, v24
	v_rcp_f32_e32 v25, v25
	v_pk_mul_f32 v[20:21], v[20:21], v[26:27]
	v_pk_mul_f32 v[22:23], v[24:25], v[22:23]
	s_nop 0
	v_pk_mul_f32 v[20:21], v[22:23], v[20:21]
	s_nop 0
	v_cvt_pk_bf16_f32 v19, v20, v21
	global_load_dwordx4 v[20:23], v[176:177], off offset:384
	ds_write_b64 v239, v[18:19]
	ds_read_b64 v[18:19], v240
	s_waitcnt lgkmcnt(0)
	v_lshlrev_b32_e32 v24, 16, v18
	v_and_b32_e32 v25, 0xffff0000, v18
	v_mul_f32_e32 v18, 0xbfb8aa3b, v24
	v_exp_f32_e32 v18, v18
	s_waitcnt vmcnt(0)
	v_pk_mul_f32 v[2:3], v[20:21], v[2:3]
	v_add_f32_e32 v18, 1.0, v18
	v_rcp_f32_e32 v26, v18
	v_mul_f32_e32 v18, 0xbfb8aa3b, v25
	v_exp_f32_e32 v18, v18
	v_pk_mul_f32 v[4:5], v[22:23], v[4:5]
	v_add_f32_e32 v18, 1.0, v18
	v_rcp_f32_e32 v27, v18
	v_lshlrev_b32_e32 v18, 16, v19
	v_and_b32_e32 v19, 0xffff0000, v19
	v_pk_mul_f32 v[20:21], v[26:27], v[24:25]
	s_nop 0
	v_pk_mul_f32 v[2:3], v[20:21], v[2:3]
	v_mul_f32_e32 v20, 0xbfb8aa3b, v18
	v_mul_f32_e32 v21, 0xbfb8aa3b, v19
	v_exp_f32_e32 v20, v20
	v_exp_f32_e32 v21, v21
	v_cvt_pk_bf16_f32 v2, v2, v3
	v_add_f32_e32 v20, 1.0, v20
	v_add_f32_e32 v21, 1.0, v21
	v_rcp_f32_e32 v20, v20
	v_rcp_f32_e32 v21, v21
	s_nop 0
	v_pk_mul_f32 v[18:19], v[20:21], v[18:19]
	s_nop 0
	v_pk_mul_f32 v[4:5], v[18:19], v[4:5]
	global_load_dwordx4 v[18:21], v[176:177], off offset:416
	v_cvt_pk_bf16_f32 v3, v4, v5
	ds_write_b64 v240, v[2:3]
	ds_read_b64 v[2:3], v241
	s_waitcnt lgkmcnt(0)
	v_lshlrev_b32_e32 v4, 16, v2
	v_and_b32_e32 v5, 0xffff0000, v2
	v_mul_f32_e32 v2, 0xbfb8aa3b, v4
	v_exp_f32_e32 v2, v2
	s_waitcnt vmcnt(0)
	v_pk_mul_f32 v[6:7], v[18:19], v[6:7]
	v_add_f32_e32 v2, 1.0, v2
	v_rcp_f32_e32 v22, v2
	v_mul_f32_e32 v2, 0xbfb8aa3b, v5
	v_exp_f32_e32 v2, v2
	v_pk_mul_f32 v[8:9], v[20:21], v[8:9]
	v_add_f32_e32 v2, 1.0, v2
	v_rcp_f32_e32 v23, v2
	v_lshlrev_b32_e32 v2, 16, v3
	v_and_b32_e32 v3, 0xffff0000, v3
	v_pk_mul_f32 v[4:5], v[22:23], v[4:5]
	s_nop 0
	v_pk_mul_f32 v[4:5], v[4:5], v[6:7]
	v_mul_f32_e32 v6, 0xbfb8aa3b, v2
	v_mul_f32_e32 v7, 0xbfb8aa3b, v3
	v_exp_f32_e32 v6, v6
	v_exp_f32_e32 v7, v7
	v_cvt_pk_bf16_f32 v4, v4, v5
	v_add_f32_e32 v6, 1.0, v6
	v_add_f32_e32 v7, 1.0, v7
	v_rcp_f32_e32 v6, v6
	v_rcp_f32_e32 v7, v7
	s_nop 0
	v_pk_mul_f32 v[2:3], v[6:7], v[2:3]
	s_nop 0
	v_pk_mul_f32 v[2:3], v[2:3], v[8:9]
	s_nop 0
	v_cvt_pk_bf16_f32 v5, v2, v3
	ds_write_b64 v241, v[4:5]
	global_load_dwordx4 v[4:7], v[176:177], off offset:448
	ds_read_b64 v[2:3], v242
	s_waitcnt lgkmcnt(0)
	v_lshlrev_b32_e32 v8, 16, v2
	v_and_b32_e32 v9, 0xffff0000, v2
	v_mul_f32_e32 v2, 0xbfb8aa3b, v8
	v_exp_f32_e32 v2, v2
	s_waitcnt vmcnt(0)
	v_pk_mul_f32 v[4:5], v[4:5], v[10:11]
	v_add_f32_e32 v2, 1.0, v2
	v_rcp_f32_e32 v18, v2
	v_mul_f32_e32 v2, 0xbfb8aa3b, v9
	v_exp_f32_e32 v2, v2
	v_pk_mul_f32 v[10:11], v[12:13], v[66:67] op_sel_hi:[1,0]
	v_pk_mul_f32 v[12:13], v[14:15], v[66:67] op_sel_hi:[1,0]
	v_pk_mul_f32 v[6:7], v[6:7], v[10:11]
	v_add_f32_e32 v2, 1.0, v2
	v_rcp_f32_e32 v19, v2
	v_lshlrev_b32_e32 v2, 16, v3
	v_and_b32_e32 v3, 0xffff0000, v3
	v_pk_mul_f32 v[8:9], v[18:19], v[8:9]
	s_nop 0
	v_pk_mul_f32 v[4:5], v[4:5], v[8:9]
	v_mul_f32_e32 v8, 0xbfb8aa3b, v2
	v_mul_f32_e32 v9, 0xbfb8aa3b, v3
	v_exp_f32_e32 v8, v8
	v_exp_f32_e32 v9, v9
	v_cvt_pk_bf16_f32 v4, v4, v5
	v_add_f32_e32 v8, 1.0, v8
	v_add_f32_e32 v9, 1.0, v9
	v_rcp_f32_e32 v8, v8
	v_rcp_f32_e32 v9, v9
	s_nop 0
	v_pk_mul_f32 v[2:3], v[8:9], v[2:3]
	s_nop 0
	v_pk_mul_f32 v[2:3], v[6:7], v[2:3]
	ds_read_b64 v[6:7], v243
	v_cvt_pk_bf16_f32 v5, v2, v3
	ds_write_b64 v242, v[4:5]
	global_load_dwordx4 v[2:5], v[176:177], off offset:480
	s_waitcnt lgkmcnt(1)
	v_lshlrev_b32_e32 v8, 16, v6
	v_and_b32_e32 v9, 0xffff0000, v6
	v_mul_f32_e32 v6, 0xbfb8aa3b, v8
	v_exp_f32_e32 v6, v6
	s_waitcnt vmcnt(0)
	v_pk_mul_f32 v[2:3], v[2:3], v[12:13]
	v_add_f32_e32 v6, 1.0, v6
	v_rcp_f32_e32 v10, v6
	v_mul_f32_e32 v6, 0xbfb8aa3b, v9
	v_exp_f32_e32 v6, v6
	s_nop 0
	v_add_f32_e32 v6, 1.0, v6
	v_rcp_f32_e32 v11, v6
	v_lshlrev_b32_e32 v6, 16, v7
	v_and_b32_e32 v7, 0xffff0000, v7
	v_pk_mul_f32 v[8:9], v[10:11], v[8:9]
	s_nop 0
	v_pk_mul_f32 v[2:3], v[2:3], v[8:9]
	v_mul_f32_e32 v8, 0xbfb8aa3b, v6
	v_mul_f32_e32 v9, 0xbfb8aa3b, v7
	v_exp_f32_e32 v8, v8
	v_exp_f32_e32 v9, v9
	v_pk_mul_f32 v[10:11], v[16:17], v[66:67] op_sel_hi:[1,0]
	v_cvt_pk_bf16_f32 v2, v2, v3
	v_add_f32_e32 v8, 1.0, v8
	v_add_f32_e32 v9, 1.0, v9
	v_rcp_f32_e32 v8, v8
	v_rcp_f32_e32 v9, v9
	v_pk_mul_f32 v[4:5], v[4:5], v[10:11]
	v_pk_mul_f32 v[6:7], v[8:9], v[6:7]
	s_nop 0
	v_pk_mul_f32 v[4:5], v[4:5], v[6:7]
	v_lshl_add_u64 v[6:7], v[174:175], 0, s[4:5]
	v_cvt_pk_bf16_f32 v3, v4, v5
	ds_write_b64 v243, v[2:3]
	ds_read2_b64 v[2:5], v228 offset1:1
	v_lshl_add_u64 v[8:9], v[6:7], 0, v[190:191]
	s_mov_b64 s[4:5], 0
	s_waitcnt lgkmcnt(0)
	global_store_dwordx4 v[8:9], v[2:5], off
	ds_read2_b64 v[2:5], v229 offset1:1
	v_lshl_add_u64 v[8:9], v[6:7], 0, v[192:193]
	s_waitcnt lgkmcnt(0)
	global_store_dwordx4 v[8:9], v[2:5], off
	ds_read2_b64 v[2:5], v229 offset0:132 offset1:133
	v_lshl_add_u64 v[8:9], v[6:7], 0, v[194:195]
	s_waitcnt lgkmcnt(0)
	global_store_dwordx4 v[8:9], v[2:5], off
	ds_read2_b64 v[2:5], v67 offset1:1
	v_lshl_add_u64 v[8:9], v[6:7], 0, v[196:197]
	s_waitcnt lgkmcnt(0)
	global_store_dwordx4 v[8:9], v[2:5], off
	ds_read2_b64 v[2:5], v68 offset1:1
	v_lshl_add_u64 v[8:9], v[6:7], 0, v[198:199]
	s_waitcnt lgkmcnt(0)
	global_store_dwordx4 v[8:9], v[2:5], off
	ds_read2_b64 v[2:5], v70 offset1:1
	v_lshl_add_u64 v[8:9], v[6:7], 0, v[200:201]
	s_waitcnt lgkmcnt(0)
	global_store_dwordx4 v[8:9], v[2:5], off
	ds_read2_b64 v[2:5], v71 offset1:1
	v_lshl_add_u64 v[8:9], v[6:7], 0, v[202:203]
	v_lshl_add_u64 v[6:7], v[6:7], 0, v[204:205]
	s_waitcnt lgkmcnt(0)
	global_store_dwordx4 v[8:9], v[2:5], off
	ds_read2_b64 v[2:5], v69 offset1:1
	s_waitcnt lgkmcnt(0)
	global_store_dwordx4 v[6:7], v[2:5], off
	s_cbranch_vccz .LBB0_641

.LBB0_709:
	s_add_i32 s9, s10, 1
	s_bitcmp1_b32 s9, 0
	s_cselect_b32 s11, 0xac00, 0
	s_add_i32 s11, s11, 0
	v_add_u32_e32 v247, s11, v227
	v_add_u32_e32 v248, s11, v228
	v_add_u32_e32 v249, s11, v229
	v_add_u32_e32 v250, s11, v200
	v_add_u32_e32 v251, s11, v202
	s_cmp_lt_u32 s10, s7
	s_cselect_b64 s[16:17], -1, 0
	s_cmp_lg_u64 s[16:17], 0
	s_addc_u32 s6, s6, 0
	s_mov_b32 s22, s14
	s_mov_b32 s23, s15
	s_mov_b32 s26, s14
	s_mov_b32 s27, s15
	s_cmp_gt_i32 s10, s1
	s_cbranch_scc1 .Lattn2_stage_only
	s_bitcmp1_b32 s10, 0
	s_cselect_b32 s10, 0xac00, 0
	s_add_i32 s10, s10, 0
	v_mov_b32_e32 v80, v213
	v_add3_u32 v0, s10, v180, v206
	ds_read_b128 v[2:5], v0
	ds_read_b128 v[6:9], v0 offset:32
	ds_read_b128 v[10:13], v0 offset:64
	ds_read_b128 v[184:187], v0 offset:96
	ds_read_b128 v[188:191], v0 offset:128
	ds_read_b128 v[192:195], v0 offset:160
	v_mov_b32_e32 v81, v80
	v_mov_b32_e32 v82, v80
	v_mov_b32_e32 v83, v80
	v_mov_b32_e32 v84, v80
	v_mov_b32_e32 v85, v80
	v_mov_b32_e32 v86, v80
	v_mov_b32_e32 v87, v80
	v_mov_b32_e32 v88, v80
	v_mov_b32_e32 v89, v80
	v_mov_b32_e32 v90, v80
	v_mov_b32_e32 v91, v80
	v_mov_b32_e32 v92, v80
	v_mov_b32_e32 v93, v80
	v_mov_b32_e32 v94, v80
	v_mov_b32_e32 v95, v80
	ds_read_b128 v[196:199], v0 offset:192
	s_waitcnt lgkmcnt(6)
	v_mfma_f32_32x32x16_bf16 v[96:111], v[2:5], v[132:135], v[80:95]
	s_mul_i32 s11, s6, 0x6000
	s_waitcnt vmcnt(4)
	ds_write_b128 v247, v[112:115]
	buffer_load_dwordx4 v[112:115], v207, s[20:23], s11 offen
	ds_read_b128 v[2:5], v0 offset:224
	s_waitcnt lgkmcnt(6)
	v_mfma_f32_32x32x16_bf16 v[96:111], v[6:9], v[136:139], v[96:111]
	ds_read_b128 v[6:9], v0 offset:256
	s_waitcnt lgkmcnt(6)
	v_mfma_f32_32x32x16_bf16 v[96:111], v[10:13], v[140:143], v[96:111]
	s_add_i32 s16, s11, 0x2000
	s_waitcnt vmcnt(4)
	ds_write_b128 v248, v[116:119]
	buffer_load_dwordx4 v[116:119], v207, s[20:23], s16 offen
	ds_read_b128 v[10:13], v0 offset:288
	s_waitcnt lgkmcnt(6)
	v_mfma_f32_32x32x16_bf16 v[96:111], v[184:187], v[144:147], v[96:111]
	ds_read_b128 v[184:187], v0 offset:320
	s_waitcnt lgkmcnt(6)
	v_mfma_f32_32x32x16_bf16 v[96:111], v[188:191], v[148:151], v[96:111]
	s_addk_i32 s11, 0x4000
	s_waitcnt vmcnt(4)
	ds_write_b128 v249, v[120:123]
	buffer_load_dwordx4 v[120:123], v207, s[20:23], s11 offen
	ds_read_b128 v[188:191], v0 offset:352
	s_waitcnt lgkmcnt(6)
	v_mfma_f32_32x32x16_bf16 v[96:111], v[192:195], v[152:155], v[96:111]
	ds_read_b128 v[192:195], v0 offset:12800
	s_waitcnt lgkmcnt(6)
	v_mfma_f32_32x32x16_bf16 v[96:111], v[196:199], v[156:159], v[96:111]
	s_lshl_b32 s11, s6, 7
	s_waitcnt vmcnt(4)
	ds_write_b128 v250, v[124:127] offset:25600
	buffer_load_dwordx4 v[124:127], v209, s[24:27], s11 offen
	ds_read_b128 v[196:199], v0 offset:12832
	s_waitcnt lgkmcnt(6)
	v_mfma_f32_32x32x16_bf16 v[96:111], v[2:5], v[160:163], v[96:111]
	ds_read_b128 v[2:5], v0 offset:12864
	s_waitcnt lgkmcnt(6)
	v_mfma_f32_32x32x16_bf16 v[96:111], v[6:9], v[164:167], v[96:111]
	s_add_i32 s11, s11, 0x100000
	s_waitcnt vmcnt(4)
	ds_write_b128 v251, v[128:131] offset:25600
	buffer_load_dwordx4 v[128:131], v209, s[24:27], s11 offen
	ds_read_b128 v[6:9], v0 offset:12896
	s_waitcnt lgkmcnt(6)
	v_mfma_f32_32x32x16_bf16 v[96:111], v[10:13], v[172:175], v[96:111]
	ds_read_b128 v[10:13], v0 offset:12928
	s_waitcnt lgkmcnt(6)
	v_mfma_f32_32x32x16_bf16 v[96:111], v[184:187], v[168:171], v[96:111]
	ds_read_b128 v[184:187], v0 offset:12960
	s_waitcnt lgkmcnt(6)
	v_mfma_f32_32x32x16_bf16 v[96:111], v[188:191], v[176:179], v[96:111]
	ds_read_b128 v[188:191], v0 offset:12992
	s_waitcnt lgkmcnt(6)
	v_mfma_f32_32x32x16_bf16 v[80:95], v[192:195], v[132:135], v[80:95]
	s_nop 8
	v_exp_f32_e32 v203, v96
	v_exp_f32_e32 v208, v97
	ds_read_b128 v[192:195], v0 offset:13024
	s_waitcnt lgkmcnt(6)
	v_mfma_f32_32x32x16_bf16 v[80:95], v[196:199], v[136:139], v[80:95]
	v_add_f32_e32 v14, v208, v203
	v_add_f32_e32 v96, v182, v14
	ds_read_b128 v[196:199], v0 offset:13056
	s_waitcnt lgkmcnt(6)
	v_mfma_f32_32x32x16_bf16 v[80:95], v[2:5], v[140:143], v[80:95]
	v_exp_f32_e32 v15, v98
	v_exp_f32_e32 v183, v99
	v_exp_f32_e32 v14, v100
	v_exp_f32_e32 v182, v101
	ds_read_b128 v[2:5], v0 offset:13088
	s_waitcnt lgkmcnt(6)
	v_mfma_f32_32x32x16_bf16 v[80:95], v[6:9], v[144:147], v[80:95]
	v_add_f32_e64 v6, v182, v14
	v_add_f32_e64 v7, v183, v15
	v_add_f32_e32 v7, v7, v96
	v_add_f32_e32 v98, v6, v7
	ds_read_b128 v[6:9], v0 offset:13120
	s_waitcnt lgkmcnt(6)
	v_mfma_f32_32x32x16_bf16 v[80:95], v[10:13], v[148:151], v[80:95]
	v_exp_f32_e32 v231, v102
	v_exp_f32_e32 v233, v103
	v_exp_f32_e32 v230, v104
	v_exp_f32_e32 v232, v105
	ds_read_b128 v[10:13], v0 offset:13152
	s_waitcnt lgkmcnt(6)
	v_mfma_f32_32x32x16_bf16 v[80:95], v[184:187], v[152:155], v[80:95]
	v_add_f32_e64 v96, v232, v230
	v_add_f32_e64 v97, v233, v231
	v_add_f32_e32 v0, v97, v98
	v_add_f32_e32 v0, v96, v0
	v_add3_u32 v234, s10, v181, v206
	ds_read_b128 v[96:99], v234 offset:25600
	s_waitcnt lgkmcnt(6)
	v_mfma_f32_32x32x16_bf16 v[80:95], v[188:191], v[156:159], v[80:95]
	v_exp_f32_e32 v187, v106
	v_exp_f32_e32 v189, v107
	v_exp_f32_e32 v186, v108
	v_exp_f32_e32 v188, v109
	ds_read_b128 v[100:103], v234 offset:30208
	s_waitcnt lgkmcnt(6)
	v_mfma_f32_32x32x16_bf16 v[80:95], v[192:195], v[160:163], v[80:95]
	v_add_f32_e64 v104, v188, v186
	v_add_f32_e64 v105, v189, v187
	v_add_f32_e32 v0, v105, v0
	v_add_f32_e32 v190, v104, v0
	ds_read_b128 v[104:107], v234 offset:34816
	s_waitcnt lgkmcnt(6)
	v_mfma_f32_32x32x16_bf16 v[80:95], v[196:199], v[164:167], v[80:95]
	v_exp_f32_e32 v192, v110
	v_exp_f32_e32 v194, v111
	ds_read_b128 v[108:111], v234 offset:39424
	s_waitcnt lgkmcnt(6)
	v_mfma_f32_32x32x16_bf16 v[80:95], v[2:5], v[172:175], v[80:95]
	v_cvt_pk_bf16_f32 v2, v203, v208
	v_cvt_pk_bf16_f32 v3, v15, v183
	v_cvt_pk_bf16_f32 v4, v14, v182
	v_cvt_pk_bf16_f32 v5, v231, v233
	ds_read_b128 v[182:185], v234 offset:25632
	s_waitcnt lgkmcnt(6)
	v_mfma_f32_32x32x16_bf16 v[80:95], v[6:9], v[168:171], v[80:95]
	v_cvt_pk_bf16_f32 v6, v230, v232
	v_cvt_pk_bf16_f32 v7, v187, v189
	v_cvt_pk_bf16_f32 v8, v186, v188
	ds_read_b128 v[186:189], v234 offset:30240
	s_waitcnt lgkmcnt(6)
	v_mfma_f32_32x32x16_bf16 v[80:95], v[10:13], v[176:179], v[80:95]
	s_waitcnt lgkmcnt(5)
	v_mfma_f32_32x32x16_bf16 v[64:79], v[96:99], v[2:5], v[64:79]
	ds_read_b128 v[10:13], v234 offset:34848
	s_waitcnt lgkmcnt(5)
	v_mfma_f32_32x32x16_bf16 v[48:63], v[100:103], v[2:5], v[48:63]
	s_nop 6
	v_exp_f32_e32 v195, v80
	v_exp_f32_e32 v193, v81
	ds_read_b128 v[96:99], v234 offset:39456
	v_exp_f32_e32 v191, v82
	v_cvt_pk_bf16_f32 v9, v192, v194
	v_pk_add_f32 v[14:15], v[194:195], v[192:193]
	s_nop 0
	v_pk_add_f32 v[14:15], v[190:191], v[14:15]
	s_waitcnt lgkmcnt(5)
	v_mfma_f32_32x32x16_bf16 v[32:47], v[104:107], v[2:5], v[32:47]
	ds_read_b128 v[100:103], v234 offset:25664
	v_exp_f32_e32 v0, v83
	v_exp_f32_e32 v190, v84
	v_exp_f32_e32 v105, v85
	v_add_f32_e32 v107, v0, v190
	s_waitcnt lgkmcnt(5)
	v_mfma_f32_32x32x16_bf16 v[16:31], v[108:111], v[2:5], v[16:31]
	ds_read_b128 v[80:83], v234 offset:30272
	v_exp_f32_e32 v106, v86
	v_exp_f32_e32 v104, v87
	s_nop 0
	v_pk_add_f32 v[108:109], v[104:105], v[106:107]
	s_waitcnt lgkmcnt(5)
	v_mfma_f32_32x32x16_bf16 v[64:79], v[182:185], v[6:9], v[64:79]
	ds_read_b128 v[2:5], v234 offset:34880
	v_exp_f32_e32 v111, v88
	v_exp_f32_e32 v185, v89
	s_waitcnt lgkmcnt(5)
	v_mfma_f32_32x32x16_bf16 v[48:63], v[186:189], v[6:9], v[48:63]
	v_exp_f32_e32 v110, v90
	v_exp_f32_e32 v184, v91
	ds_read_b128 v[84:87], v234 offset:39488
	v_pk_add_f32 v[182:183], v[184:185], v[110:111]
	s_waitcnt lgkmcnt(5)
	v_mfma_f32_32x32x16_bf16 v[32:47], v[10:13], v[6:9], v[32:47]
	ds_read_b128 v[88:91], v234 offset:25696
	v_exp_f32_e32 v187, v92
	v_exp_f32_e32 v189, v93
	s_waitcnt lgkmcnt(5)
	v_mfma_f32_32x32x16_bf16 v[16:31], v[96:99], v[6:9], v[16:31]
	v_exp_f32_e32 v186, v94
	v_exp_f32_e32 v188, v95
	v_add_f32_e32 v92, v14, v15
	v_add_f32_e32 v92, v109, v92
	v_add_f32_e32 v6, v108, v92
	ds_read_b128 v[10:13], v234 offset:30304
	v_add_f32_e32 v6, v183, v6
	v_pk_add_f32 v[14:15], v[188:189], v[186:187]
	v_add_f32_e32 v6, v182, v6
	v_add_f32_e32 v6, v15, v6
	v_add_f32_e32 v182, v14, v6
	v_cvt_pk_bf16_f32 v6, v195, v193
	v_cvt_pk_bf16_f32 v7, v191, v0
	v_cvt_pk_bf16_f32 v8, v190, v105
	v_cvt_pk_bf16_f32 v9, v106, v104
	v_cvt_pk_bf16_f32 v92, v111, v185
	v_cvt_pk_bf16_f32 v93, v110, v184
	v_cvt_pk_bf16_f32 v94, v187, v189
	v_cvt_pk_bf16_f32 v95, v186, v188
	s_waitcnt lgkmcnt(5)
	v_mfma_f32_32x32x16_bf16 v[64:79], v[100:103], v[6:9], v[64:79]
	ds_read_b128 v[96:99], v234 offset:34912
	s_waitcnt lgkmcnt(5)
	v_mfma_f32_32x32x16_bf16 v[48:63], v[80:83], v[6:9], v[48:63]
	ds_read_b128 v[100:103], v234 offset:39520
	s_waitcnt lgkmcnt(5)
	v_mfma_f32_32x32x16_bf16 v[32:47], v[2:5], v[6:9], v[32:47]
	s_waitcnt lgkmcnt(4)
	v_mfma_f32_32x32x16_bf16 v[16:31], v[84:87], v[6:9], v[16:31]
	s_waitcnt lgkmcnt(3)
	v_mfma_f32_32x32x16_bf16 v[64:79], v[88:91], v[92:95], v[64:79]
	s_waitcnt lgkmcnt(2)
	v_mfma_f32_32x32x16_bf16 v[48:63], v[10:13], v[92:95], v[48:63]
	s_waitcnt lgkmcnt(1)
	v_mfma_f32_32x32x16_bf16 v[32:47], v[96:99], v[92:95], v[32:47]
	s_waitcnt lgkmcnt(0)
	v_mfma_f32_32x32x16_bf16 v[16:31], v[100:103], v[92:95], v[16:31]

.Lattn2_stage_only:
	s_mul_i32 s11, s6, 0x6000
	s_waitcnt vmcnt(4)
	ds_write_b128 v247, v[112:115]
	buffer_load_dwordx4 v[112:115], v207, s[20:23], s11 offen
	s_add_i32 s16, s11, 0x2000
	s_waitcnt vmcnt(4)
	ds_write_b128 v248, v[116:119]
	buffer_load_dwordx4 v[116:119], v207, s[20:23], s16 offen
	s_addk_i32 s11, 0x4000
	s_waitcnt vmcnt(4)
	ds_write_b128 v249, v[120:123]
	buffer_load_dwordx4 v[120:123], v207, s[20:23], s11 offen
	s_lshl_b32 s11, s6, 7
	s_waitcnt vmcnt(4)
	ds_write_b128 v250, v[124:127] offset:25600
	buffer_load_dwordx4 v[124:127], v209, s[24:27], s11 offen
	s_add_i32 s11, s11, 0x100000
	s_waitcnt vmcnt(4)
	ds_write_b128 v251, v[128:131] offset:25600
	buffer_load_dwordx4 v[128:131], v209, s[24:27], s11 offen
	s_branch .LBB0_711

	.amdhsa_kernel _Z8fwd_mega6Params
		.amdhsa_group_segment_fixed_size 0
		.amdhsa_private_segment_fixed_size 0
		.amdhsa_kernarg_size 400
		.amdhsa_user_sgpr_count 2
		.amdhsa_user_sgpr_dispatch_ptr 0
		.amdhsa_user_sgpr_queue_ptr 0
		.amdhsa_user_sgpr_kernarg_segment_ptr 1
		.amdhsa_user_sgpr_dispatch_id 0
		.amdhsa_user_sgpr_kernarg_preload_length 0
		.amdhsa_user_sgpr_kernarg_preload_offset 0
		.amdhsa_user_sgpr_private_segment_size 0
		.amdhsa_uses_dynamic_stack 0
		.amdhsa_enable_private_segment 0
		.amdhsa_system_sgpr_workgroup_id_x 1
		.amdhsa_system_sgpr_workgroup_id_y 0
		.amdhsa_system_sgpr_workgroup_id_z 0
		.amdhsa_system_sgpr_workgroup_info 0
		.amdhsa_system_vgpr_workitem_id 2
		.amdhsa_next_free_vgpr 252
		.amdhsa_next_free_sgpr 98
		.amdhsa_accum_offset 252
		.amdhsa_reserve_vcc 1
		.amdhsa_float_round_mode_32 0
		.amdhsa_float_round_mode_16_64 0
		.amdhsa_float_denorm_mode_32 3
		.amdhsa_float_denorm_mode_16_64 3
		.amdhsa_dx10_clamp 1
		.amdhsa_ieee_mode 1
		.amdhsa_fp16_overflow 0
		.amdhsa_tg_split 0
		.amdhsa_exception_fp_ieee_invalid_op 0
		.amdhsa_exception_fp_denorm_src 0
		.amdhsa_exception_fp_ieee_div_zero 0
		.amdhsa_exception_fp_ieee_overflow 0
		.amdhsa_exception_fp_ieee_underflow 0
		.amdhsa_exception_fp_ieee_inexact 0
		.amdhsa_exception_int_div_zero 0
	.end_amdhsa_kernel

amdhsa.kernels:
  - .agpr_count:     0
    .args:
      - .offset:         0
        .size:           144
        .value_kind:     by_value
      - .offset:         144
        .size:           4
        .value_kind:     hidden_block_count_x
      - .offset:         148
        .size:           4
        .value_kind:     hidden_block_count_y
      - .offset:         152
        .size:           4
        .value_kind:     hidden_block_count_z
      - .offset:         156
        .size:           2
        .value_kind:     hidden_group_size_x
      - .offset:         158
        .size:           2
        .value_kind:     hidden_group_size_y
      - .offset:         160
        .size:           2
        .value_kind:     hidden_group_size_z
      - .offset:         162
        .size:           2
        .value_kind:     hidden_remainder_x
      - .offset:         164
        .size:           2
        .value_kind:     hidden_remainder_y
      - .offset:         166
        .size:           2
        .value_kind:     hidden_remainder_z
      - .offset:         184
        .size:           8
        .value_kind:     hidden_global_offset_x
      - .offset:         192
        .size:           8
        .value_kind:     hidden_global_offset_y
      - .offset:         200
        .size:           8
        .value_kind:     hidden_global_offset_z
      - .offset:         208
        .size:           2
        .value_kind:     hidden_grid_dims
      - .offset:         232
        .size:           8
        .value_kind:     hidden_multigrid_sync_arg
      - .offset:         264
        .size:           4
        .value_kind:     hidden_dynamic_lds_size
    .group_segment_fixed_size: 0
    .kernarg_segment_align: 8
    .kernarg_segment_size: 400
    .language:       OpenCL C
    .language_version:
      - 2
      - 0
    .max_flat_workgroup_size: 512
    .name:           _Z8fwd_mega6Params
    .private_segment_fixed_size: 0
    .sgpr_count:     104
    .sgpr_spill_count: 212
    .symbol:         _Z8fwd_mega6Params.kd
    .uniform_work_group_size: 1
    .uses_dynamic_stack: false
    .vgpr_count:     252
    .vgpr_spill_count: 0
    .wavefront_size: 64
